# MoBA gathered loop unrolled by two with K fragments prefetched two tiles ahead (alternating register buffers)
# speedup vs baseline: 1.0172x; 1.0002x over previous
; DI void tile_gload(TileRegs& t, const bf16_t* K, const bf16_t* V, int kbase, int kstride, int lane) {
;     const int row0 = lane >> 3, ch = lane & 7;
; #pragma unroll
;     for (int i = 0; i < 4; ++i) {
;         const unsigned off = (unsigned)((kbase + kstride * (row0 + 8 * i)) * 128 + ch * 16);
;         t.k[i] = *(const u32x4*)((const unsigned char*)K + off); t.v[i] = *(const u32x4*)((const unsigned char*)V + off);
;     }
; DI void attn_b_item(unsigned char* ws, LAS unsigned char* buf, LAS unsigned char* qbuf, LAS unsigned* tbl, LAS float* km  , int bh, int qblk, int w4, int lane) {
;     ...
;     if (cmask) {
;         int n = __builtin_ctz(cmask);
;         tile_gload(tr, K, V, n * 256, 1, lane);
;         for (;;) {
;             const unsigned rest = cmask & ~((2u << n) - 1u);
;             const int nn = rest ? __builtin_ctz(rest) : -1;
.LBB0_571:
	s_waitcnt vmcnt(0)
	s_cmp_eq_u32 s56, 0
	s_cbranch_scc1 .LBB0_519
	s_ff1_i32_b32 s88, s56
	v_mbcnt_hi_u32_b32 v193, -1, v224
	v_lshlrev_b32_e32 v191, 4, v193
	v_and_b32_e32 v190, 31, v193
	v_lshrrev_b32_e32 v192, 5, v193
	v_lshlrev_b32_e32 v190, 7, v190
	v_lshl_or_b32 v190, v192, 4, v190
	s_lshl_b32 s16, s88, 15
	v_add_u32_e32 v193, s16, v191
	v_add_u32_e32 v192, s16, v190
	global_load_dwordx4 v[116:119], v193, s[78:79]
	global_load_dwordx4 v[120:123], v193, s[78:79] offset:1024
	global_load_dwordx4 v[124:127], v193, s[78:79] offset:2048
	global_load_dwordx4 v[128:131], v193, s[78:79] offset:3072
	v_add_u32_e32 v192, 0x1000, v193
	global_load_dwordx4 v[194:197], v192, s[78:79]
	global_load_dwordx4 v[198:201], v192, s[78:79] offset:1024
	global_load_dwordx4 v[202:205], v192, s[78:79] offset:2048
	global_load_dwordx4 v[206:209], v192, s[78:79] offset:3072
	global_load_dwordx4 v[132:135], v193, s[80:81]
	global_load_dwordx4 v[136:139], v193, s[80:81] offset:1024
	global_load_dwordx4 v[140:143], v193, s[80:81] offset:2048
	global_load_dwordx4 v[144:147], v193, s[80:81] offset:3072
	s_lshl_b32 s16, s44, 19
	s_lshl_b32 s17, s84, 22
	s_or_b32 s16, s17, s16
	s_add_u32 s82, s50, s16
	s_addc_u32 s83, s51, 0

; #define LAS __attribute__((address_space(3)))
; #define MFMA32(a, b, c) __builtin_amdgcn_mfma_f32_32x32x16_bf16((a), (b), (c), 0, 0, 0)
; DI void core1g(ASt& st, const bf16x8 (&qf)[4], LAS unsigned char* buf, bool ok, float m0, int lane) {
;     const int r = lane & 31, h = lane >> 5;
;     f32x16 s;
;     {
;         const f32x16 zero = {0.f, 0.f, 0.f, 0.f, 0.f, 0.f, 0.f, 0.f, 0.f, 0.f, 0.f, 0.f, 0.f, 0.f, 0.f, 0.f};
;         const bf16x8 kf = lds_frag(buf + r * TROW + h * 16); s = MFMA32(kf, qf[0], zero);
;     }
; #pragma unroll
;     for (int ks = 1; ks < 4; ++ks) { const bf16x8 kf = lds_frag(buf + r * TROW + (2 * ks + h) * 16); s = MFMA32(kf, qf[ks], s); }
;     LAS unsigned char* vb = buf + 32 * TROW + (4 * h + ((lane & 15) >> 2)) * TROW + 32 * ((lane >> 4) & 1) + 8 * (lane & 3);
;     softmax_p<true>(st, s, 0, 0, 0, ok, false, m0);
;     bf16x8 p[2]; pack_p(p, s, ok);
; #pragma unroll
;     for (int s2 = 0; s2 < 2; ++s2) {
;         const bf16x8 v0 = load_vfrag1(vb, 0, s2), v1 = load_vfrag1(vb, 1, s2);
;         st.o0 = MFMA32(v0, p[s2], st.o0); st.o1 = MFMA32(v1, p[s2], st.o1);
;     }
; }
; DI void attn_b_item(unsigned char* ws, LAS unsigned char* buf, LAS unsigned char* qbuf, LAS unsigned* tbl, LAS float* km  , int bh, int qblk, int w4, int lane) {
;     ...
;             for (int T = 0; T < 8; ++T) {
;                 tile_lds_write(buf, tr, lane);
;                 if (T < 7) tile_gload(tr, K, V, n * 256 + 32 * (T + 1), 1, lane);
;                 else if (nn >= 0) tile_gload(tr, K, V, nn * 256, 1, lane);
;                 core1g(g, gq, buf, okg, m0, lane);
;             }
.LBB0_581:
	s_lshl_b32 s91, s57, 15
	s_cmp_lg_u64 s[86:87], 0
	s_cselect_b32 s91, s91, s89
	s_add_i32 s90, s88, 0x1000
	s_cmpk_lt_u32 s90, 0x8000
	s_cselect_b32 s82, s89, s91
	s_and_b32 s90, s90, 0x7fff
	s_add_i32 s90, s90, s82
	s_add_i32 s83, s88, 0x2000
	s_cmpk_lt_u32 s83, 0x8000
	s_cselect_b32 s82, s89, s91
	s_and_b32 s83, s83, 0x7fff
	s_add_i32 s83, s83, s82
	s_add_i32 s88, s88, 0x1000
	s_waitcnt vmcnt(8)
	v_mfma_f32_32x32x16_bf16 v[96:111], v[116:119], v[148:151], 0
	v_mfma_f32_32x32x16_bf16 v[96:111], v[120:123], v[152:155], v[96:111]
	v_add_u32_e32 v193, s90, v191
	v_mfma_f32_32x32x16_bf16 v[96:111], v[124:127], v[156:159], v[96:111]
	v_add_u32_e32 v192, s83, v191
	v_mfma_f32_32x32x16_bf16 v[96:111], v[128:131], v[160:163], v[96:111]
	global_load_dwordx4 v[116:119], v192, s[78:79]
	global_load_dwordx4 v[120:123], v192, s[78:79] offset:1024
	global_load_dwordx4 v[124:127], v192, s[78:79] offset:2048
	global_load_dwordx4 v[128:131], v192, s[78:79] offset:3072
	s_nop 7
	v_sub_f32_e32 v96, v96, v247
	v_sub_f32_e32 v97, v97, v247
	v_sub_f32_e32 v98, v98, v247
	v_sub_f32_e32 v99, v99, v247
	v_exp_f32_e32 v96, v96
	v_exp_f32_e32 v97, v97
	v_sub_f32_e32 v100, v100, v247
	v_sub_f32_e32 v101, v101, v247
	v_exp_f32_e32 v98, v98
	v_exp_f32_e32 v99, v99
	v_sub_f32_e32 v102, v102, v247
	v_sub_f32_e32 v103, v103, v247
	v_exp_f32_e32 v100, v100
	v_exp_f32_e32 v101, v101
	v_sub_f32_e32 v104, v104, v247
	v_sub_f32_e32 v105, v105, v247
	v_sub_f32_e32 v108, v108, v247
	v_sub_f32_e32 v109, v109, v247
	v_exp_f32_e32 v102, v102
	v_exp_f32_e32 v103, v103
	v_exp_f32_e32 v104, v104
	v_exp_f32_e32 v105, v105
	v_exp_f32_e32 v168, v108
	v_exp_f32_e32 v169, v109
	v_pk_add_f32 v[108:109], v[96:97], 0 op_sel_hi:[1,0]
	v_cvt_pk_bf16_f32 v96, v96, v97
	v_cvt_pk_bf16_f32 v97, v98, v99
	v_pk_add_f32 v[98:99], v[98:99], v[108:109]
	v_sub_f32_e32 v106, v106, v247
	v_pk_add_f32 v[98:99], v[100:101], v[98:99]
	v_sub_f32_e32 v107, v107, v247
	v_pk_add_f32 v[98:99], v[102:103], v[98:99]
	v_sub_f32_e32 v110, v110, v247
	v_pk_add_f32 v[108:109], v[104:105], v[98:99]
	v_cvt_pk_bf16_f32 v98, v100, v101
	v_cvt_pk_bf16_f32 v99, v102, v103
	v_sub_f32_e32 v111, v111, v247
	v_exp_f32_e32 v106, v106
	v_exp_f32_e32 v107, v107
	v_exp_f32_e32 v170, v110
	v_exp_f32_e32 v171, v111
	v_cndmask_b32_e64 v96, 0, v96, s[20:21]
	v_cndmask_b32_e64 v97, 0, v97, s[20:21]
	v_cndmask_b32_e64 v98, 0, v98, s[20:21]
	v_cndmask_b32_e64 v99, 0, v99, s[20:21]
	v_pk_add_f32 v[108:109], v[106:107], v[108:109]
	v_cvt_pk_bf16_f32 v104, v104, v105
	s_waitcnt vmcnt(7)
	v_mfma_f32_32x32x16_bf16 v[64:79], v[132:135], v[96:99], v[64:79]
	v_cvt_pk_bf16_f32 v105, v106, v107
	v_add_f32_e64 v164, v168, v108
	v_add_f32_e64 v165, v169, v109
	v_cndmask_b32_e64 v104, 0, v104, s[20:21]
	v_cndmask_b32_e64 v105, 0, v105, s[20:21]
	s_waitcnt vmcnt(5)
	v_mfma_f32_32x32x16_bf16 v[80:95], v[140:143], v[96:99], v[80:95]
	v_cvt_pk_bf16_f32 v96, v168, v169
	v_cndmask_b32_e64 v106, 0, v96, s[20:21]
	v_cvt_pk_bf16_f32 v96, v170, v171
	v_cndmask_b32_e64 v107, 0, v96, s[20:21]
	v_pk_add_f32 v[100:101], v[170:171], v[164:165]
	s_nop 0
	v_mfma_f32_32x32x16_bf16 v[64:79], v[136:139], v[104:107], v[64:79]
	v_add_f32_e32 v100, v100, v101
	v_cndmask_b32_e64 v100, 0, v100, s[20:21]
	v_add_f32_e32 v112, v112, v100
	s_waitcnt vmcnt(4)
; #define LAS __attribute__((address_space(3)))
; #define MFMA32(a, b, c) __builtin_amdgcn_mfma_f32_32x32x16_bf16((a), (b), (c), 0, 0, 0)
; DI void core1g(ASt& st, const bf16x8 (&qf)[4], LAS unsigned char* buf, bool ok, float m0, int lane) {
;     const int r = lane & 31, h = lane >> 5;
;     f32x16 s;
;     {
;         const f32x16 zero = {0.f, 0.f, 0.f, 0.f, 0.f, 0.f, 0.f, 0.f, 0.f, 0.f, 0.f, 0.f, 0.f, 0.f, 0.f, 0.f};
;         const bf16x8 kf = lds_frag(buf + r * TROW + h * 16); s = MFMA32(kf, qf[0], zero);
;     }
; #pragma unroll
;     for (int ks = 1; ks < 4; ++ks) { const bf16x8 kf = lds_frag(buf + r * TROW + (2 * ks + h) * 16); s = MFMA32(kf, qf[ks], s); }
;     LAS unsigned char* vb = buf + 32 * TROW + (4 * h + ((lane & 15) >> 2)) * TROW + 32 * ((lane >> 4) & 1) + 8 * (lane & 3);
;     softmax_p<true>(st, s, 0, 0, 0, ok, false, m0);
;     bf16x8 p[2]; pack_p(p, s, ok);
; #pragma unroll
;     for (int s2 = 0; s2 < 2; ++s2) {
;         const bf16x8 v0 = load_vfrag1(vb, 0, s2), v1 = load_vfrag1(vb, 1, s2);
;         st.o0 = MFMA32(v0, p[s2], st.o0); st.o1 = MFMA32(v1, p[s2], st.o1);
;     }
; }
; DI void attn_b_item(unsigned char* ws, LAS unsigned char* buf, LAS unsigned char* qbuf, LAS unsigned* tbl, LAS float* km  , int bh, int qblk, int w4, int lane) {
;     ...
;             for (int T = 0; T < 8; ++T) {
;                 tile_lds_write(buf, tr, lane);
;                 if (T < 7) tile_gload(tr, K, V, n * 256 + 32 * (T + 1), 1, lane);
;                 else if (nn >= 0) tile_gload(tr, K, V, nn * 256, 1, lane);
;                 core1g(g, gq, buf, okg, m0, lane);
;             }
	v_mfma_f32_32x32x16_bf16 v[80:95], v[144:147], v[104:107], v[80:95]
	global_load_dwordx4 v[132:135], v193, s[80:81]
	global_load_dwordx4 v[136:139], v193, s[80:81] offset:1024
	global_load_dwordx4 v[140:143], v193, s[80:81] offset:2048
	global_load_dwordx4 v[144:147], v193, s[80:81] offset:3072
	s_lshl_b32 s91, s57, 15
	s_cmp_lg_u64 s[86:87], 0
	s_cselect_b32 s91, s91, s89
	s_add_i32 s90, s88, 0x1000
	s_cmpk_lt_u32 s90, 0x8000
	s_cselect_b32 s82, s89, s91
	s_and_b32 s90, s90, 0x7fff
	s_add_i32 s90, s90, s82
	s_add_i32 s83, s88, 0x2000
	s_cmpk_lt_u32 s83, 0x8000
	s_cselect_b32 s82, s89, s91
	s_and_b32 s83, s83, 0x7fff
	s_add_i32 s83, s83, s82
	s_add_i32 s88, s88, 0x1000
	s_cmpk_eq_u32 s88, 0x8000
	s_waitcnt vmcnt(8)
	v_mfma_f32_32x32x16_bf16 v[96:111], v[194:197], v[148:151], 0
	v_mfma_f32_32x32x16_bf16 v[96:111], v[198:201], v[152:155], v[96:111]
	v_add_u32_e32 v193, s90, v191
	v_mfma_f32_32x32x16_bf16 v[96:111], v[202:205], v[156:159], v[96:111]
	v_add_u32_e32 v192, s83, v191
	v_mfma_f32_32x32x16_bf16 v[96:111], v[206:209], v[160:163], v[96:111]
	global_load_dwordx4 v[194:197], v192, s[78:79]
	global_load_dwordx4 v[198:201], v192, s[78:79] offset:1024
	global_load_dwordx4 v[202:205], v192, s[78:79] offset:2048
	global_load_dwordx4 v[206:209], v192, s[78:79] offset:3072
	s_nop 7
	v_sub_f32_e32 v96, v96, v247
	v_sub_f32_e32 v97, v97, v247
	v_sub_f32_e32 v98, v98, v247
	v_sub_f32_e32 v99, v99, v247
	v_exp_f32_e32 v96, v96
	v_exp_f32_e32 v97, v97
	v_sub_f32_e32 v100, v100, v247
	v_sub_f32_e32 v101, v101, v247
	v_exp_f32_e32 v98, v98
	v_exp_f32_e32 v99, v99
	v_sub_f32_e32 v102, v102, v247
	v_sub_f32_e32 v103, v103, v247
	v_exp_f32_e32 v100, v100
	v_exp_f32_e32 v101, v101
	v_sub_f32_e32 v104, v104, v247
	v_sub_f32_e32 v105, v105, v247
	v_sub_f32_e32 v108, v108, v247
	v_sub_f32_e32 v109, v109, v247
	v_exp_f32_e32 v102, v102
	v_exp_f32_e32 v103, v103
	v_exp_f32_e32 v104, v104
	v_exp_f32_e32 v105, v105
	v_exp_f32_e32 v168, v108
	v_exp_f32_e32 v169, v109
	v_pk_add_f32 v[108:109], v[96:97], 0 op_sel_hi:[1,0]
	v_cvt_pk_bf16_f32 v96, v96, v97
	v_cvt_pk_bf16_f32 v97, v98, v99
	v_pk_add_f32 v[98:99], v[98:99], v[108:109]
	v_sub_f32_e32 v106, v106, v247
	v_pk_add_f32 v[98:99], v[100:101], v[98:99]
	v_sub_f32_e32 v107, v107, v247
	v_pk_add_f32 v[98:99], v[102:103], v[98:99]
	v_sub_f32_e32 v110, v110, v247
	v_pk_add_f32 v[108:109], v[104:105], v[98:99]
	v_cvt_pk_bf16_f32 v98, v100, v101
	v_cvt_pk_bf16_f32 v99, v102, v103
	v_sub_f32_e32 v111, v111, v247
	v_exp_f32_e32 v106, v106
	v_exp_f32_e32 v107, v107
	v_exp_f32_e32 v170, v110
	v_exp_f32_e32 v171, v111
	v_cndmask_b32_e64 v96, 0, v96, s[20:21]
	v_cndmask_b32_e64 v97, 0, v97, s[20:21]
	v_cndmask_b32_e64 v98, 0, v98, s[20:21]
	v_cndmask_b32_e64 v99, 0, v99, s[20:21]
	v_pk_add_f32 v[108:109], v[106:107], v[108:109]
	v_cvt_pk_bf16_f32 v104, v104, v105
	s_waitcnt vmcnt(7)
	v_mfma_f32_32x32x16_bf16 v[64:79], v[132:135], v[96:99], v[64:79]
	v_cvt_pk_bf16_f32 v105, v106, v107
	v_add_f32_e64 v164, v168, v108
	v_add_f32_e64 v165, v169, v109
	v_cndmask_b32_e64 v104, 0, v104, s[20:21]
	v_cndmask_b32_e64 v105, 0, v105, s[20:21]
	s_waitcnt vmcnt(5)
	v_mfma_f32_32x32x16_bf16 v[80:95], v[140:143], v[96:99], v[80:95]
	v_cvt_pk_bf16_f32 v96, v168, v169
	v_cndmask_b32_e64 v106, 0, v96, s[20:21]
	v_cvt_pk_bf16_f32 v96, v170, v171
	v_cndmask_b32_e64 v107, 0, v96, s[20:21]
	v_pk_add_f32 v[100:101], v[170:171], v[164:165]
	s_nop 0
	v_mfma_f32_32x32x16_bf16 v[64:79], v[136:139], v[104:107], v[64:79]
	v_add_f32_e32 v100, v100, v101
	v_cndmask_b32_e64 v100, 0, v100, s[20:21]
	v_add_f32_e32 v112, v112, v100
	s_waitcnt vmcnt(4)
	v_mfma_f32_32x32x16_bf16 v[80:95], v[144:147], v[104:107], v[80:95]
	global_load_dwordx4 v[132:135], v193, s[80:81]
	global_load_dwordx4 v[136:139], v193, s[80:81] offset:1024
	global_load_dwordx4 v[140:143], v193, s[80:81] offset:2048
	global_load_dwordx4 v[144:147], v193, s[80:81] offset:3072
	s_cbranch_scc1 .LBB0_589
	s_branch .LBB0_581
